# chain step: first 8 LDS operand reads issued right after the step barrier, ahead of prefetch address arithmetic and global loads (address temps renamed to v242-245)
# speedup vs baseline: 1.0030x; 1.0000x over previous
.LBB0_201:
	v_add_u32_e32 v190, 0x2000, v224
	ds_read2_b64 v[66:69], v224 offset1:2
	ds_read2_b64 v[170:173], v224 offset0:4 offset1:6
	ds_read2_b64 v[70:73], v190 offset0:64 offset1:66
	ds_read2_b64 v[174:177], v190 offset0:68 offset1:70
	ds_read2_b64 v[178:181], v224 offset0:8 offset1:10
	ds_read2_b64 v[182:185], v190 offset0:72 offset1:74
	ds_read2_b64 v[234:237], v224 offset0:12 offset1:14
	ds_read2_b64 v[238:241], v190 offset0:76 offset1:78
	s_add_i32 s0, s8, -1
	v_mov_b32_e32 v242, s0
	s_min_u32 s2, s0, s52
	v_sub_u32_e64 v242, s52, v242 clamp
	s_and_b64 s[0:1], s[4:5], exec
	v_readfirstlane_b32 s0, v242
	s_cselect_b32 s0, s2, s0
	s_add_i32 s2, s0, s37
	v_lshl_add_u32 v244, s2, 6, v218
	v_mad_i64_i32 v[242:243], s[0:1], v244, s28, v[200:201]
	v_add_u32_e32 v244, 32, v244
	v_mad_i64_i32 v[244:245], s[0:1], v244, s28, v[200:201]
	s_lshl_b32 s0, s2, 2
	s_or_b32 s0, s0, s12
	s_ashr_i32 s1, s0, 31
	s_lshl_b64 s[2:3], s[0:1], 14
	s_add_u32 s2, s36, s2
	s_addc_u32 s3, s13, s3
	global_load_dwordx4 v[154:157], v[242:243], off
	global_load_dwordx4 v[158:161], v[244:245], off
	v_lshl_add_u64 v[242:243], v[188:189], 1, s[2:3]
	v_lshl_add_u64 v[242:243], v[242:243], 0, v[0:1]
	v_lshl_add_u64 v[244:245], v[198:199], 1, s[2:3]
	v_lshl_add_u64 v[244:245], v[244:245], 0, v[0:1]
	global_load_dwordx4 v[162:165], v[242:243], off
	global_load_dwordx4 v[166:169], v[244:245], off
	s_and_saveexec_b64 s[2:3], vcc
	s_cbranch_execz .LBB0_203
	s_lshl_b64 s[14:15], s[0:1], 9
	v_lshl_add_u64 v[242:243], v[204:205], 0, s[14:15]
	global_load_dwordx4 v[98:101], v[242:243], off
.LBB0_203:
	s_or_b64 exec, exec, s[2:3]
	s_add_i32 s7, s8, -3
	s_and_b64 s[2:3], s[4:5], exec
	s_cselect_b32 s2, s7, s6
	s_add_i32 s2, s2, s37
	v_cvt_pk_bf16_f32 v74, v50, v51
	v_cvt_pk_bf16_f32 v75, v52, v53
	v_cvt_pk_bf16_f32 v76, v54, v55
	v_cvt_pk_bf16_f32 v77, v56, v57
	v_cvt_pk_bf16_f32 v242, v58, v59
	v_cvt_pk_bf16_f32 v243, v60, v61
	s_waitcnt lgkmcnt(7)
	v_mfma_f32_32x32x16_bf16 v[82:97], v[74:77], v[66:69], 0
	v_cvt_pk_bf16_f32 v244, v62, v63
	v_cvt_pk_bf16_f32 v245, v64, v65
	s_waitcnt lgkmcnt(5)
	v_mfma_f32_32x32x16_bf16 v[66:81], v[74:77], v[70:73], 0
	v_mfma_f32_32x32x16_bf16 v[82:97], v[242:245], v[170:173], v[82:97]
	s_waitcnt lgkmcnt(4)
	v_mfma_f32_32x32x16_bf16 v[66:81], v[242:245], v[174:177], v[66:81]
	ds_read2_b64 v[170:173], v224 offset0:16 offset1:18
	ds_read2_b64 v[174:177], v224 offset0:20 offset1:22
	ds_read2_b64 v[242:245], v190 offset0:80 offset1:82
	ds_read2_b64 v[246:249], v190 offset0:84 offset1:86
	v_cvt_pk_bf16_f32 v194, v34, v35
	v_cvt_pk_bf16_f32 v195, v36, v37
	v_cvt_pk_bf16_f32 v196, v38, v39
	v_cvt_pk_bf16_f32 v197, v40, v41
	s_waitcnt lgkmcnt(7)
	s_nop 0
	v_mfma_f32_32x32x16_bf16 v[82:97], v[194:197], v[178:181], v[82:97]
	v_cvt_pk_bf16_f32 v178, v42, v43
	v_cvt_pk_bf16_f32 v179, v44, v45
	v_cvt_pk_bf16_f32 v180, v46, v47
	v_cvt_pk_bf16_f32 v181, v48, v49
	s_waitcnt lgkmcnt(6)
	v_mfma_f32_32x32x16_bf16 v[66:81], v[194:197], v[182:185], v[66:81]
	s_waitcnt lgkmcnt(5)
	v_mfma_f32_32x32x16_bf16 v[82:97], v[178:181], v[234:237], v[82:97]
	s_waitcnt lgkmcnt(4)
	v_mfma_f32_32x32x16_bf16 v[66:81], v[178:181], v[238:241], v[66:81]
	ds_read2_b64 v[194:197], v224 offset0:24 offset1:26
	ds_read2_b64 v[234:237], v224 offset0:28 offset1:30
	ds_read2_b64 v[238:241], v190 offset0:88 offset1:90
	ds_read2_b64 v[190:193], v190 offset0:92 offset1:94
	v_cvt_pk_bf16_f32 v178, v18, v19
	v_cvt_pk_bf16_f32 v179, v20, v21
	v_cvt_pk_bf16_f32 v180, v22, v23
	v_cvt_pk_bf16_f32 v181, v24, v25
	s_waitcnt lgkmcnt(7)
	s_nop 0
	v_mfma_f32_32x32x16_bf16 v[82:97], v[178:181], v[170:173], v[82:97]
	v_cvt_pk_bf16_f32 v170, v26, v27
	v_cvt_pk_bf16_f32 v171, v28, v29
	v_cvt_pk_bf16_f32 v172, v30, v31
	v_cvt_pk_bf16_f32 v173, v32, v33
	s_waitcnt lgkmcnt(5)
	v_mfma_f32_32x32x16_bf16 v[66:81], v[178:181], v[242:245], v[66:81]
	v_mfma_f32_32x32x16_bf16 v[82:97], v[170:173], v[174:177], v[82:97]
	s_waitcnt lgkmcnt(4)
	v_mfma_f32_32x32x16_bf16 v[66:81], v[170:173], v[246:249], v[66:81]
	ds_read_b128 v[182:185], v221 offset:35840
	ds_read_b128 v[178:181], v221 offset:35872
	ds_read_b128 v[174:177], v221 offset:35904
	ds_read_b128 v[170:173], v221 offset:35936
	v_cvt_pk_bf16_f32 v242, v2, v3
	v_cvt_pk_bf16_f32 v243, v4, v5
	v_cvt_pk_bf16_f32 v244, v6, v7
	v_cvt_pk_bf16_f32 v245, v8, v9
	s_waitcnt lgkmcnt(7)
	s_nop 0
	v_mfma_f32_32x32x16_bf16 v[82:97], v[242:245], v[194:197], v[82:97]
	v_cvt_pk_bf16_f32 v194, v10, v11
	v_cvt_pk_bf16_f32 v195, v12, v13
	v_cvt_pk_bf16_f32 v196, v14, v15
	v_cvt_pk_bf16_f32 v197, v16, v17
	s_waitcnt lgkmcnt(5)
	v_mfma_f32_32x32x16_bf16 v[66:81], v[242:245], v[238:241], v[66:81]
	v_mfma_f32_32x32x16_bf16 v[82:97], v[194:197], v[234:237], v[82:97]
	s_waitcnt lgkmcnt(4)
	v_mfma_f32_32x32x16_bf16 v[66:81], v[194:197], v[190:193], v[66:81]
	ds_read_b128 v[242:245], v226 offset:17408
	ds_read_b128 v[246:249], v226 offset:17440
	ds_read_b128 v[190:193], v221 offset:35968
	ds_read_b128 v[194:197], v221 offset:36000
	ds_read_b128 v[234:237], v221 offset:36032
	ds_read_b128 v[238:241], v221 offset:36064
	s_waitcnt lgkmcnt(9)
	v_mul_f32_e32 v52, v52, v184
	v_mul_f32_e32 v53, v53, v185
	s_waitcnt lgkmcnt(8)
	v_mul_f32_e32 v56, v56, v180
	v_mul_f32_e32 v57, v57, v181
	s_waitcnt lgkmcnt(7)
	v_mul_f32_e32 v60, v60, v176
	v_mul_f32_e32 v61, v61, v177
	s_waitcnt lgkmcnt(6)
	v_mul_f32_e32 v64, v64, v172
	v_mul_f32_e32 v65, v65, v173
	v_mul_f32_e32 v62, v62, v170
	v_mul_f32_e32 v63, v63, v171
	v_mul_f32_e32 v58, v58, v174
	v_mul_f32_e32 v59, v59, v175
	v_mul_f32_e32 v54, v54, v178
	v_mul_f32_e32 v55, v55, v179
	v_mul_f32_e32 v50, v50, v182
	v_mul_f32_e32 v51, v51, v183
	ds_read_b128 v[182:185], v221 offset:36096
	ds_read_b128 v[178:181], v221 offset:36128
	ds_read_b128 v[174:177], v221 offset:36160
	ds_read_b128 v[170:173], v221 offset:36192
	s_waitcnt lgkmcnt(7)
	v_mul_f32_e32 v36, v36, v192
	v_mul_f32_e32 v37, v37, v193
	s_waitcnt lgkmcnt(6)
	v_mul_f32_e32 v40, v40, v196
	v_mul_f32_e32 v41, v41, v197
	s_waitcnt lgkmcnt(5)
	v_mul_f32_e32 v44, v44, v236
	v_mul_f32_e32 v45, v45, v237
	s_waitcnt lgkmcnt(4)
	v_mul_f32_e32 v48, v48, v240
	v_mul_f32_e32 v49, v49, v241
	v_mul_f32_e32 v46, v46, v238
	v_mul_f32_e32 v47, v47, v239
	v_mul_f32_e32 v42, v42, v234
	v_mul_f32_e32 v43, v43, v235
	v_mul_f32_e32 v38, v38, v194
	v_mul_f32_e32 v39, v39, v195
	v_mul_f32_e32 v34, v34, v190
	v_mul_f32_e32 v35, v35, v191
	ds_read_b128 v[190:193], v221 offset:36224
	ds_read_b128 v[194:197], v221 offset:36256
	ds_read_b128 v[234:237], v221 offset:36288
	ds_read_b128 v[238:241], v221 offset:36320
	s_waitcnt lgkmcnt(7)
	v_mul_f32_e32 v20, v20, v184
	v_mul_f32_e32 v21, v21, v185
	s_waitcnt lgkmcnt(6)
	v_mul_f32_e32 v24, v24, v180
	v_mul_f32_e32 v25, v25, v181
	s_waitcnt lgkmcnt(5)
	v_mul_f32_e32 v28, v28, v176
	v_mul_f32_e32 v29, v29, v177
	s_waitcnt lgkmcnt(4)
	v_mul_f32_e32 v32, v32, v172
	v_mul_f32_e32 v33, v33, v173
	v_mul_f32_e32 v30, v30, v170
	v_mul_f32_e32 v31, v31, v171
	v_mul_f32_e32 v26, v26, v174
	v_mul_f32_e32 v27, v27, v175
	v_mul_f32_e32 v22, v22, v178
	v_mul_f32_e32 v23, v23, v179
	v_mul_f32_e32 v18, v18, v182
	v_mul_f32_e32 v19, v19, v183
	ds_read_b128 v[174:177], v226 offset:17472
	ds_read_b128 v[170:173], v226 offset:17504
	s_waitcnt lgkmcnt(5)
	v_mul_f32_e32 v4, v4, v192
	v_mul_f32_e32 v5, v5, v193
	s_waitcnt lgkmcnt(4)
	v_mul_f32_e32 v8, v8, v196
	v_mul_f32_e32 v9, v9, v197
	s_waitcnt lgkmcnt(3)
	v_mul_f32_e32 v12, v12, v236
	v_mul_f32_e32 v13, v13, v237
	s_waitcnt lgkmcnt(2)
	v_mul_f32_e32 v16, v16, v240
	v_mul_f32_e32 v17, v17, v241
	v_mul_f32_e32 v14, v14, v238
	v_mul_f32_e32 v15, v15, v239
	v_mul_f32_e32 v10, v10, v234
	v_mul_f32_e32 v11, v11, v235
	v_mul_f32_e32 v6, v6, v194
	v_mul_f32_e32 v7, v7, v195
	v_mul_f32_e32 v2, v2, v190
	v_mul_f32_e32 v3, v3, v191
	ds_read_b128 v[190:193], v227 offset:17408
	ds_read_b128 v[194:197], v227 offset:17440
	ds_read_b128 v[234:237], v227 offset:17472
	ds_read_b128 v[238:241], v227 offset:17504
	s_waitcnt vmcnt(15)
	v_mfma_f32_32x32x16_bf16 v[50:65], v[242:245], v[114:117], v[50:65]
	s_waitcnt vmcnt(14)
	v_mfma_f32_32x32x16_bf16 v[50:65], v[246:249], v[110:113], v[50:65]
	s_waitcnt vmcnt(13) lgkmcnt(5)
	v_mfma_f32_32x32x16_bf16 v[50:65], v[174:177], v[106:109], v[50:65]
	s_waitcnt vmcnt(12) lgkmcnt(4)
	v_mfma_f32_32x32x16_bf16 v[50:65], v[170:173], v[102:105], v[50:65]
	v_lshl_or_b32 v242, s2, 6, v219
	v_ashrrev_i32_e32 v243, 31, v242
	v_lshlrev_b64 v[244:245], 11, v[242:243]
	v_lshl_add_u64 v[244:245], v[202:203], 0, v[244:245]
	v_cvt_pk_bf16_f32 v82, v82, v83
	v_cvt_pk_bf16_f32 v83, v84, v85
	v_cvt_pk_bf16_f32 v84, v90, v91
	v_cvt_pk_bf16_f32 v85, v92, v93
	v_cvt_pk_bf16_f32 v86, v86, v87
	v_cvt_pk_bf16_f32 v87, v88, v89
	v_cvt_pk_bf16_f32 v88, v94, v95
	v_cvt_pk_bf16_f32 v89, v96, v97
	v_or_b32_e32 v90, 32, v242
	v_ashrrev_i32_e32 v91, 31, v90
	v_permlane32_swap_b32_e32 v82, v84
	v_permlane32_swap_b32_e32 v83, v85
	v_permlane32_swap_b32_e32 v86, v88
	v_permlane32_swap_b32_e32 v87, v89
	global_store_dwordx4 v[244:245], v[82:85], off
	global_store_dwordx4 v[244:245], v[86:89], off offset:16
	v_lshlrev_b64 v[90:91], 11, v[90:91]
	v_lshl_add_u64 v[90:91], v[202:203], 0, v[90:91]
	v_cvt_pk_bf16_f32 v66, v66, v67
	v_cvt_pk_bf16_f32 v67, v68, v69
	v_cvt_pk_bf16_f32 v68, v74, v75
	v_cvt_pk_bf16_f32 v69, v76, v77
	v_cvt_pk_bf16_f32 v70, v70, v71
	v_cvt_pk_bf16_f32 v71, v72, v73
	v_cvt_pk_bf16_f32 v72, v78, v79
	v_cvt_pk_bf16_f32 v73, v80, v81
	s_nop 1
	v_permlane32_swap_b32_e32 v66, v68
	v_permlane32_swap_b32_e32 v67, v69
	v_permlane32_swap_b32_e32 v70, v72
	v_permlane32_swap_b32_e32 v71, v73
	global_store_dwordx4 v[90:91], v[66:69], off
	global_store_dwordx4 v[90:91], v[70:73], off offset:16
	s_waitcnt vmcnt(15)
	ds_write_b128 v187, v[118:121] offset:36864
	s_waitcnt vmcnt(14)
	ds_write_b128 v187, v[122:125] offset:45568
	s_waitcnt vmcnt(13)
	ds_write_b128 v220, v[130:133] offset:54272
	s_waitcnt vmcnt(12)
	ds_write_b128 v220, v[134:137] offset:63488
	s_and_saveexec_b64 s[14:15], vcc
	v_add_u32_e32 v66, 0x11c00, v228
	ds_write_b128 v66, v[126:129]
	s_or_b64 exec, exec, s[14:15]
	ds_read_b128 v[170:173], v225 offset:26624
	ds_read_b128 v[174:177], v225 offset:26656
	ds_read_b128 v[178:181], v225 offset:26688
	ds_read_b128 v[182:185], v225 offset:26720
	s_waitcnt lgkmcnt(7)
	v_mfma_f32_32x32x16_bf16 v[34:49], v[190:193], v[114:117], v[34:49]
	s_waitcnt lgkmcnt(6)
	v_mfma_f32_32x32x16_bf16 v[34:49], v[194:197], v[110:113], v[34:49]
	s_waitcnt lgkmcnt(5)
	v_mfma_f32_32x32x16_bf16 v[34:49], v[234:237], v[106:109], v[34:49]
	s_waitcnt lgkmcnt(4)
	v_mfma_f32_32x32x16_bf16 v[34:49], v[238:241], v[102:105], v[34:49]
	ds_read_b128 v[190:193], v225 offset:31232
	ds_read_b128 v[194:197], v225 offset:31264
	ds_read_b128 v[234:237], v225 offset:31296
	ds_read_b128 v[238:241], v225 offset:31328
	s_waitcnt lgkmcnt(7)
	v_mfma_f32_32x32x16_bf16 v[18:33], v[170:173], v[114:117], v[18:33]
	s_waitcnt lgkmcnt(6)
	v_mfma_f32_32x32x16_bf16 v[18:33], v[174:177], v[110:113], v[18:33]
	s_waitcnt lgkmcnt(5)
	v_mfma_f32_32x32x16_bf16 v[18:33], v[178:181], v[106:109], v[18:33]
	s_waitcnt lgkmcnt(4)
	v_mfma_f32_32x32x16_bf16 v[18:33], v[182:185], v[102:105], v[18:33]
	s_waitcnt lgkmcnt(3)
	v_mfma_f32_32x32x16_bf16 v[2:17], v[190:193], v[114:117], v[2:17]
	s_waitcnt lgkmcnt(2)
	v_mfma_f32_32x32x16_bf16 v[2:17], v[194:197], v[110:113], v[2:17]
	s_waitcnt lgkmcnt(1)
	v_mfma_f32_32x32x16_bf16 v[2:17], v[234:237], v[106:109], v[2:17]
	s_waitcnt lgkmcnt(0)
	v_mfma_f32_32x32x16_bf16 v[2:17], v[238:241], v[102:105], v[2:17]
	s_lshl_b64 s[0:1], s[0:1], 15
	v_lshl_add_u64 v[102:103], v[206:207], 0, s[0:1]
	global_load_dwordx4 v[114:117], v[102:103], off
	global_load_dwordx4 v[110:113], v[102:103], off offset:32
	global_load_dwordx4 v[106:109], v[102:103], off offset:64
	s_nop 0
	global_load_dwordx4 v[102:105], v[102:103], off offset:96
	v_mov_b32_e32 v242, s8
	s_min_u32 s2, s8, s52
	v_sub_u32_e64 v242, s52, v242 clamp
	s_and_b64 s[0:1], s[4:5], exec
	v_readfirstlane_b32 s0, v242
	s_cselect_b32 s0, s2, s0
	s_add_i32 s2, s0, s37
	v_lshl_add_u32 v244, s2, 6, v218
	v_mad_i64_i32 v[242:243], s[0:1], v244, s28, v[200:201]
	v_add_u32_e32 v244, 32, v244
	v_mad_i64_i32 v[244:245], s[0:1], v244, s28, v[200:201]
	s_lshl_b32 s0, s2, 2
	s_or_b32 s0, s0, s12
	s_ashr_i32 s1, s0, 31
	s_lshl_b64 s[2:3], s[0:1], 14
	s_add_u32 s2, s36, s2
	s_addc_u32 s3, s13, s3
	s_waitcnt lgkmcnt(0)
	s_barrier
	v_add_u32_e32 v229, 0x9000, v224
	v_add_u32_e32 v246, 0xb000, v224
	ds_read2_b64 v[66:69], v229 offset1:2
	ds_read2_b64 v[170:173], v229 offset0:4 offset1:6
	ds_read2_b64 v[70:73], v246 offset0:64 offset1:66
	ds_read2_b64 v[174:177], v246 offset0:68 offset1:70
	ds_read2_b64 v[178:181], v229 offset0:8 offset1:10
	ds_read2_b64 v[182:185], v246 offset0:72 offset1:74
	ds_read2_b64 v[190:193], v229 offset0:12 offset1:14
	ds_read2_b64 v[194:197], v246 offset0:76 offset1:78
	global_load_dwordx4 v[118:121], v[242:243], off
	global_load_dwordx4 v[122:125], v[244:245], off
	v_lshl_add_u64 v[242:243], v[188:189], 1, s[2:3]
	v_lshl_add_u64 v[242:243], v[242:243], 0, v[0:1]
	v_lshl_add_u64 v[244:245], v[198:199], 1, s[2:3]
	v_lshl_add_u64 v[244:245], v[244:245], 0, v[0:1]
	global_load_dwordx4 v[130:133], v[242:243], off
	global_load_dwordx4 v[134:137], v[244:245], off
	s_and_saveexec_b64 s[2:3], vcc
	s_cbranch_execz .LBB0_207
	s_lshl_b64 s[14:15], s[0:1], 9
	v_lshl_add_u64 v[242:243], v[204:205], 0, s[14:15]
	global_load_dwordx4 v[126:129], v[242:243], off
.LBB0_207:
	s_or_b64 exec, exec, s[2:3]
	s_xor_b32 s2, s7, 0x3fffffe
	s_add_i32 s3, s2, s81
	s_add_i32 s2, s7, 1
	s_and_b64 s[14:15], s[4:5], exec
	s_cselect_b32 s3, s2, s3
	s_add_i32 s3, s3, s37
	v_cvt_pk_bf16_f32 v74, v50, v51
	v_cvt_pk_bf16_f32 v75, v52, v53
	v_cvt_pk_bf16_f32 v76, v54, v55
	v_cvt_pk_bf16_f32 v77, v56, v57
	v_cvt_pk_bf16_f32 v234, v58, v59
	v_cvt_pk_bf16_f32 v235, v60, v61
	s_waitcnt lgkmcnt(7)
	v_mfma_f32_32x32x16_bf16 v[82:97], v[74:77], v[66:69], 0
	v_cvt_pk_bf16_f32 v236, v62, v63
	v_cvt_pk_bf16_f32 v237, v64, v65
	s_waitcnt lgkmcnt(5)
	v_mfma_f32_32x32x16_bf16 v[66:81], v[74:77], v[70:73], 0
	v_mfma_f32_32x32x16_bf16 v[82:97], v[234:237], v[170:173], v[82:97]
	s_waitcnt lgkmcnt(4)
	v_mfma_f32_32x32x16_bf16 v[66:81], v[234:237], v[174:177], v[66:81]
	ds_read2_b64 v[170:173], v229 offset0:16 offset1:18
	ds_read2_b64 v[174:177], v229 offset0:20 offset1:22
	ds_read2_b64 v[234:237], v246 offset0:80 offset1:82
	ds_read2_b64 v[238:241], v246 offset0:84 offset1:86
	v_cvt_pk_bf16_f32 v242, v34, v35
	v_cvt_pk_bf16_f32 v243, v36, v37
	v_cvt_pk_bf16_f32 v244, v38, v39
	v_cvt_pk_bf16_f32 v245, v40, v41
	s_waitcnt lgkmcnt(7)
	s_nop 0
	v_mfma_f32_32x32x16_bf16 v[82:97], v[242:245], v[178:181], v[82:97]
	v_cvt_pk_bf16_f32 v178, v42, v43
	v_cvt_pk_bf16_f32 v179, v44, v45
	v_cvt_pk_bf16_f32 v180, v46, v47
	v_cvt_pk_bf16_f32 v181, v48, v49
	s_waitcnt lgkmcnt(6)
	v_mfma_f32_32x32x16_bf16 v[66:81], v[242:245], v[182:185], v[66:81]
	s_waitcnt lgkmcnt(5)
	v_mfma_f32_32x32x16_bf16 v[82:97], v[178:181], v[190:193], v[82:97]
	s_waitcnt lgkmcnt(4)
	v_mfma_f32_32x32x16_bf16 v[66:81], v[178:181], v[194:197], v[66:81]
	ds_read2_b64 v[190:193], v229 offset0:24 offset1:26
	ds_read2_b64 v[194:197], v229 offset0:28 offset1:30
	ds_read2_b64 v[242:245], v246 offset0:88 offset1:90
	ds_read2_b64 v[246:249], v246 offset0:92 offset1:94
	v_cvt_pk_bf16_f32 v178, v18, v19
	v_cvt_pk_bf16_f32 v179, v20, v21
	v_cvt_pk_bf16_f32 v180, v22, v23
	v_cvt_pk_bf16_f32 v181, v24, v25
	s_waitcnt lgkmcnt(7)
	s_nop 0
	v_mfma_f32_32x32x16_bf16 v[82:97], v[178:181], v[170:173], v[82:97]
	v_cvt_pk_bf16_f32 v170, v26, v27
	v_cvt_pk_bf16_f32 v171, v28, v29
	v_cvt_pk_bf16_f32 v172, v30, v31
	v_cvt_pk_bf16_f32 v173, v32, v33
	s_waitcnt lgkmcnt(5)
	v_mfma_f32_32x32x16_bf16 v[66:81], v[178:181], v[234:237], v[66:81]
	v_mfma_f32_32x32x16_bf16 v[82:97], v[170:173], v[174:177], v[82:97]
	s_waitcnt lgkmcnt(4)
	v_mfma_f32_32x32x16_bf16 v[66:81], v[170:173], v[238:241], v[66:81]
	v_add_u32_e32 v229, 0x11c00, v186
	ds_read_b128 v[182:185], v229
	ds_read_b128 v[178:181], v229 offset:32
	ds_read_b128 v[174:177], v229 offset:64
	ds_read_b128 v[170:173], v229 offset:96
	v_cvt_pk_bf16_f32 v234, v2, v3
	v_cvt_pk_bf16_f32 v235, v4, v5
	v_cvt_pk_bf16_f32 v236, v6, v7
	v_cvt_pk_bf16_f32 v237, v8, v9
	s_waitcnt lgkmcnt(7)
	s_nop 0
	v_mfma_f32_32x32x16_bf16 v[82:97], v[234:237], v[190:193], v[82:97]
	v_cvt_pk_bf16_f32 v190, v10, v11
	v_cvt_pk_bf16_f32 v191, v12, v13
	v_cvt_pk_bf16_f32 v192, v14, v15
	v_cvt_pk_bf16_f32 v193, v16, v17
	s_waitcnt lgkmcnt(5)
	v_mfma_f32_32x32x16_bf16 v[66:81], v[234:237], v[242:245], v[66:81]
	v_mfma_f32_32x32x16_bf16 v[82:97], v[190:193], v[194:197], v[82:97]
	s_waitcnt lgkmcnt(4)
	v_mfma_f32_32x32x16_bf16 v[66:81], v[190:193], v[246:249], v[66:81]
	ds_read_b128 v[242:245], v226 offset:54272
	ds_read_b128 v[246:249], v226 offset:54304
	ds_read_b128 v[190:193], v229 offset:128
	ds_read_b128 v[194:197], v229 offset:160
	ds_read_b128 v[234:237], v229 offset:192
	ds_read_b128 v[238:241], v229 offset:224
	s_waitcnt lgkmcnt(9)
	v_mul_f32_e32 v52, v52, v184
	v_mul_f32_e32 v53, v53, v185
	s_waitcnt lgkmcnt(8)
	v_mul_f32_e32 v54, v54, v178
	v_mul_f32_e32 v55, v55, v179
	s_waitcnt lgkmcnt(7)
	v_mul_f32_e32 v58, v58, v174
	v_mul_f32_e32 v59, v59, v175
	s_waitcnt lgkmcnt(6)
	v_mul_f32_e32 v62, v62, v170
	v_mul_f32_e32 v63, v63, v171
	v_mul_f32_e32 v64, v64, v172
	v_mul_f32_e32 v65, v65, v173
	v_mul_f32_e32 v60, v60, v176
	v_mul_f32_e32 v61, v61, v177
	v_mul_f32_e32 v56, v56, v180
	v_mul_f32_e32 v57, v57, v181
	v_mul_f32_e32 v50, v50, v182
	v_mul_f32_e32 v51, v51, v183
	ds_read_b128 v[182:185], v229 offset:256
	ds_read_b128 v[178:181], v229 offset:288
	ds_read_b128 v[174:177], v229 offset:320
	ds_read_b128 v[170:173], v229 offset:352
	s_waitcnt lgkmcnt(7)
	v_mul_f32_e32 v36, v36, v192
	v_mul_f32_e32 v37, v37, v193
	s_waitcnt lgkmcnt(6)
	v_mul_f32_e32 v38, v38, v194
	v_mul_f32_e32 v39, v39, v195
	s_waitcnt lgkmcnt(5)
	v_mul_f32_e32 v42, v42, v234
	v_mul_f32_e32 v43, v43, v235
	s_waitcnt lgkmcnt(4)
	v_mul_f32_e32 v46, v46, v238
	v_mul_f32_e32 v47, v47, v239
	v_mul_f32_e32 v48, v48, v240
	v_mul_f32_e32 v49, v49, v241
	v_mul_f32_e32 v44, v44, v236
	v_mul_f32_e32 v45, v45, v237
	v_mul_f32_e32 v40, v40, v196
	v_mul_f32_e32 v41, v41, v197
	v_mul_f32_e32 v34, v34, v190
	v_mul_f32_e32 v35, v35, v191
	ds_read_b128 v[190:193], v229 offset:384
	ds_read_b128 v[194:197], v229 offset:416
	ds_read_b128 v[234:237], v229 offset:448
	ds_read_b128 v[238:241], v229 offset:480
	s_waitcnt lgkmcnt(7)
	v_mul_f32_e32 v20, v20, v184
	v_mul_f32_e32 v21, v21, v185
	s_waitcnt lgkmcnt(6)
	v_mul_f32_e32 v22, v22, v178
	v_mul_f32_e32 v23, v23, v179
	s_waitcnt lgkmcnt(5)
	v_mul_f32_e32 v26, v26, v174
	v_mul_f32_e32 v27, v27, v175
	s_waitcnt lgkmcnt(4)
	v_mul_f32_e32 v30, v30, v170
	v_mul_f32_e32 v31, v31, v171
	v_mul_f32_e32 v32, v32, v172
	v_mul_f32_e32 v33, v33, v173
	v_mul_f32_e32 v28, v28, v176
	v_mul_f32_e32 v29, v29, v177
	v_mul_f32_e32 v24, v24, v180
	v_mul_f32_e32 v25, v25, v181
	v_mul_f32_e32 v18, v18, v182
	v_mul_f32_e32 v19, v19, v183
	ds_read_b128 v[174:177], v226 offset:54336
	ds_read_b128 v[170:173], v226 offset:54368
	s_waitcnt lgkmcnt(5)
	v_mul_f32_e32 v4, v4, v192
	v_mul_f32_e32 v5, v5, v193
	s_waitcnt lgkmcnt(4)
	v_mul_f32_e32 v6, v6, v194
	v_mul_f32_e32 v7, v7, v195
	s_waitcnt lgkmcnt(3)
	v_mul_f32_e32 v10, v10, v234
	v_mul_f32_e32 v11, v11, v235
	s_waitcnt lgkmcnt(2)
	v_mul_f32_e32 v14, v14, v238
	v_mul_f32_e32 v15, v15, v239
	v_mul_f32_e32 v16, v16, v240
	v_mul_f32_e32 v17, v17, v241
	v_mul_f32_e32 v12, v12, v236
	v_mul_f32_e32 v13, v13, v237
	v_mul_f32_e32 v8, v8, v196
	v_mul_f32_e32 v9, v9, v197
	v_mul_f32_e32 v2, v2, v190
	v_mul_f32_e32 v3, v3, v191
	ds_read_b128 v[190:193], v227 offset:54272
	ds_read_b128 v[194:197], v227 offset:54304
	ds_read_b128 v[234:237], v227 offset:54336
	ds_read_b128 v[238:241], v227 offset:54368
	s_waitcnt vmcnt(19)
	v_mfma_f32_32x32x16_bf16 v[50:65], v[242:245], v[150:153], v[50:65]
	s_waitcnt vmcnt(18)
	v_mfma_f32_32x32x16_bf16 v[50:65], v[246:249], v[146:149], v[50:65]
	s_waitcnt vmcnt(17) lgkmcnt(5)
	v_mfma_f32_32x32x16_bf16 v[50:65], v[174:177], v[142:145], v[50:65]
	s_waitcnt vmcnt(16) lgkmcnt(4)
	v_mfma_f32_32x32x16_bf16 v[50:65], v[170:173], v[138:141], v[50:65]
	v_lshl_or_b32 v242, s3, 6, v219
	v_ashrrev_i32_e32 v243, 31, v242
	v_lshlrev_b64 v[244:245], 11, v[242:243]
	v_lshl_add_u64 v[244:245], v[202:203], 0, v[244:245]
	v_cvt_pk_bf16_f32 v82, v82, v83
	v_cvt_pk_bf16_f32 v83, v84, v85
	v_cvt_pk_bf16_f32 v84, v90, v91
	v_cvt_pk_bf16_f32 v85, v92, v93
	v_cvt_pk_bf16_f32 v86, v86, v87
	v_cvt_pk_bf16_f32 v87, v88, v89
	v_cvt_pk_bf16_f32 v88, v94, v95
	v_cvt_pk_bf16_f32 v89, v96, v97
	v_or_b32_e32 v90, 32, v242
	v_ashrrev_i32_e32 v91, 31, v90
	v_permlane32_swap_b32_e32 v82, v84
	v_permlane32_swap_b32_e32 v83, v85
	v_permlane32_swap_b32_e32 v86, v88
	v_permlane32_swap_b32_e32 v87, v89
	global_store_dwordx4 v[244:245], v[82:85], off
	global_store_dwordx4 v[244:245], v[86:89], off offset:16
	v_lshlrev_b64 v[90:91], 11, v[90:91]
	v_lshl_add_u64 v[90:91], v[202:203], 0, v[90:91]
	v_cvt_pk_bf16_f32 v66, v66, v67
	v_cvt_pk_bf16_f32 v67, v68, v69
	v_cvt_pk_bf16_f32 v68, v74, v75
	v_cvt_pk_bf16_f32 v69, v76, v77
	v_cvt_pk_bf16_f32 v70, v70, v71
	v_cvt_pk_bf16_f32 v71, v72, v73
	v_cvt_pk_bf16_f32 v72, v78, v79
	v_cvt_pk_bf16_f32 v73, v80, v81
	s_nop 1
	v_permlane32_swap_b32_e32 v66, v68
	v_permlane32_swap_b32_e32 v67, v69
	v_permlane32_swap_b32_e32 v70, v72
	v_permlane32_swap_b32_e32 v71, v73
	global_store_dwordx4 v[90:91], v[66:69], off
	global_store_dwordx4 v[90:91], v[70:73], off offset:16
	s_waitcnt vmcnt(19)
	ds_write_b128 v187, v[154:157]
	s_waitcnt vmcnt(18)
	ds_write_b128 v187, v[158:161] offset:8704
	s_waitcnt vmcnt(17)
	ds_write_b128 v220, v[162:165] offset:17408
	s_waitcnt vmcnt(16)
	ds_write_b128 v220, v[166:169] offset:26624
	s_and_saveexec_b64 s[14:15], vcc
	ds_write_b128 v228, v[98:101] offset:35840
	s_or_b64 exec, exec, s[14:15]
	ds_read_b128 v[170:173], v222 offset:63488
	ds_read_b128 v[174:177], v222 offset:63520
	ds_read_b128 v[178:181], v222 offset:63552
	ds_read_b128 v[182:185], v222 offset:63584
	s_waitcnt lgkmcnt(7)
	v_mfma_f32_32x32x16_bf16 v[34:49], v[190:193], v[150:153], v[34:49]
	s_waitcnt lgkmcnt(6)
	v_mfma_f32_32x32x16_bf16 v[34:49], v[194:197], v[146:149], v[34:49]
	s_waitcnt lgkmcnt(5)
	v_mfma_f32_32x32x16_bf16 v[34:49], v[234:237], v[142:145], v[34:49]
	s_waitcnt lgkmcnt(4)
	v_mfma_f32_32x32x16_bf16 v[34:49], v[238:241], v[138:141], v[34:49]
	ds_read_b128 v[190:193], v223 offset:13824
	ds_read_b128 v[194:197], v223 offset:13856
	ds_read_b128 v[234:237], v223 offset:13888
	ds_read_b128 v[238:241], v223 offset:13920
	s_waitcnt lgkmcnt(7)
	v_mfma_f32_32x32x16_bf16 v[18:33], v[170:173], v[150:153], v[18:33]
	s_waitcnt lgkmcnt(6)
	v_mfma_f32_32x32x16_bf16 v[18:33], v[174:177], v[146:149], v[18:33]
	s_waitcnt lgkmcnt(5)
	v_mfma_f32_32x32x16_bf16 v[18:33], v[178:181], v[142:145], v[18:33]
	s_waitcnt lgkmcnt(4)
	v_mfma_f32_32x32x16_bf16 v[18:33], v[182:185], v[138:141], v[18:33]
	s_waitcnt lgkmcnt(3)
	v_mfma_f32_32x32x16_bf16 v[2:17], v[190:193], v[150:153], v[2:17]
	s_waitcnt lgkmcnt(2)
	v_mfma_f32_32x32x16_bf16 v[2:17], v[194:197], v[146:149], v[2:17]
	s_waitcnt lgkmcnt(1)
	v_mfma_f32_32x32x16_bf16 v[2:17], v[234:237], v[142:145], v[2:17]
	s_waitcnt lgkmcnt(0)
	v_mfma_f32_32x32x16_bf16 v[2:17], v[238:241], v[138:141], v[2:17]
	s_lshl_b64 s[0:1], s[0:1], 15
	v_lshl_add_u64 v[138:139], v[206:207], 0, s[0:1]
	global_load_dwordx4 v[150:153], v[138:139], off
	global_load_dwordx4 v[146:149], v[138:139], off offset:32
	global_load_dwordx4 v[142:145], v[138:139], off offset:64
	s_nop 0
	global_load_dwordx4 v[138:141], v[138:139], off offset:96
	s_branch .LBB0_200
